# mix row loop: the 49 output stores per row marked non-temporal
# speedup vs baseline: 1.0073x; 1.0045x over previous
.Lmix_nopf:
	s_nop 0
	v_mov_b32_e32 v110, v17
	s_nop 0
	v_mov_b32_e32 v111, v9
	v_mov_b32_e32 v114, v19
	v_mov_b32_e32 v115, v11
	v_mov_b32_e32 v40, v16
	v_mov_b32_e32 v41, v8
	v_mov_b32_e32 v112, v18
	v_mov_b32_e32 v113, v10
	s_nop 0
	v_pk_mul_f32 v[116:117], v[34:35], v[34:35]
	v_pk_mul_f32 v[118:119], v[32:33], v[32:33]
	v_pk_mul_f32 v[110:111], v[110:111], v[110:111]
	v_pk_mul_f32 v[114:115], v[114:115], v[114:115]
	v_pk_mov_b32 v[124:125], v[118:119], v[116:117] op_sel:[1,0]
	v_mov_b32_e32 v119, v117
	v_pk_fma_f32 v[40:41], v[40:41], v[40:41], v[110:111]
	v_pk_fma_f32 v[110:111], v[112:113], v[112:113], v[114:115]
	s_nop 0
	v_mul_f32_e32 v120, v37, v37
	v_mul_f32_e32 v122, v39, v39
	v_pk_add_f32 v[112:113], v[124:125], v[118:119]
	v_pk_add_f32 v[40:41], v[40:41], v[110:111]
	v_pk_fma_f32 v[116:117], v[36:37], v[36:37], v[120:121] op_sel_hi:[1,1,0]
	v_pk_fma_f32 v[120:121], v[38:39], v[38:39], v[122:123] op_sel_hi:[1,1,0]
	v_pk_add_f32 v[110:111], v[112:113], v[112:113] op_sel:[0,1] op_sel_hi:[1,0]
	v_pk_add_f32 v[40:41], v[40:41], v[40:41] op_sel:[0,1] op_sel_hi:[1,0]
	ds_read_b128 v[86:89], v77
	ds_read_b128 v[90:93], v77 offset:1024
	ds_read_b128 v[94:97], v82 offset:8192
	ds_read_b128 v[98:101], v82 offset:9216
	ds_read_b128 v[102:105], v82
	ds_read_b128 v[106:109], v82 offset:1024
	s_waitcnt lgkmcnt(3)
	v_pk_add_f32 v[94:95], v[94:95], 1.0 op_sel_hi:[1,0]
	s_waitcnt lgkmcnt(2)
	v_pk_add_f32 v[98:99], v[98:99], 1.0 op_sel_hi:[1,0]
	s_nop 0
	v_mul_f32_e32 v129, v20, v20
	v_mul_f32_e32 v131, v21, v21
	v_mul_f32_e32 v132, v22, v22
	v_mul_f32_e32 v133, v23, v23
	s_nop 0
	v_pk_mul_f32 v[122:123], v[14:15], v[14:15]
	v_pk_mul_f32 v[126:127], v[12:13], v[12:13]
	v_mov_b32_e32 v117, v132
	v_mov_b32_e32 v121, v133
	v_mov_b32_e32 v111, v131
	v_mov_b32_e32 v41, v129
	v_pk_mov_b32 v[114:115], v[126:127], v[122:123] op_sel:[1,0]
	v_mov_b32_e32 v127, v123
	v_pk_add_f32 v[112:113], v[116:117], v[120:121]
	v_pk_add_f32 v[40:41], v[40:41], v[110:111]
	s_nop 0
	v_mul_f32_e32 v128, v5, v5
	v_mul_f32_e32 v130, v7, v7
	v_pk_add_f32 v[114:115], v[114:115], v[126:127]
	v_pk_add_f32 v[40:41], v[40:41], v[112:113]
	v_mul_f32_e32 v134, v0, v0
	v_mul_f32_e32 v135, v1, v1
	v_mul_f32_e32 v136, v2, v2
	v_mul_f32_e32 v137, v3, v3
	v_pk_fma_f32 v[118:119], v[4:5], v[4:5], v[128:129] op_sel_hi:[1,1,0]
	v_pk_fma_f32 v[122:123], v[6:7], v[6:7], v[130:131] op_sel_hi:[1,1,0]
	v_pk_add_f32 v[114:115], v[114:115], v[114:115] op_sel:[0,1] op_sel_hi:[1,0]
	v_pk_add_f32 v[40:41], v[40:41], v[40:41] op_sel:[0,1] op_sel_hi:[1,0]
	v_mov_b32_e32 v119, v136
	v_mov_b32_e32 v123, v137
	v_mov_b32_e32 v115, v135
	v_mov_b32_e32 v41, v134
	v_pk_add_f32 v[116:117], v[118:119], v[122:123]
	v_pk_add_f32 v[40:41], v[40:41], v[114:115]
	s_nop 0
	v_pk_add_f32 v[40:41], v[40:41], v[116:117]
	ds_read_b128 v[110:113], v77 offset:2048
	ds_read_b128 v[114:117], v77 offset:3072
	ds_read_b128 v[118:121], v82 offset:10240
	ds_read_b128 v[122:125], v82 offset:11264
	v_add_f32_e32 v40, v40, v41
	ds_read_b128 v[126:129], v82 offset:2048
	ds_read_b128 v[130:133], v82 offset:3072
	v_add_f32_dpp v40, v40, v40 quad_perm:[1,0,3,2] row_mask:0xf bank_mask:0xf bound_ctrl:1
	s_waitcnt lgkmcnt(3)
	v_pk_add_f32 v[118:119], v[118:119], 1.0 op_sel_hi:[1,0]
	v_add_f32_dpp v40, v40, v40 quad_perm:[2,3,0,1] row_mask:0xf bank_mask:0xf bound_ctrl:1
	s_nop 1
	v_add_f32_dpp v40, v40, v40 row_half_mirror row_mask:0xf bank_mask:0xf bound_ctrl:1
	s_nop 1
	v_add_f32_dpp v40, v40, v40 row_mirror row_mask:0xf bank_mask:0xf bound_ctrl:1
	ds_bpermute_b32 v41, v75, v40
	s_waitcnt lgkmcnt(0)
	v_add_f32_e32 v134, v40, v41
	ds_bpermute_b32 v135, v76, v134
	v_pk_add_f32 v[40:41], v[96:97], 1.0 op_sel_hi:[1,0]
	v_pk_add_f32 v[96:97], v[100:101], 1.0 op_sel_hi:[1,0]
	s_waitcnt lgkmcnt(0)
	v_add_f32_e32 v100, v134, v135
	v_fmamk_f32 v100, v100, 0x3a000000, v81
	v_mul_f32_e32 v101, 0x4b800000, v100
	v_cmp_gt_f32_e32 vcc, s3, v100
	s_nop 1
	v_cndmask_b32_e32 v100, v100, v101, vcc
	v_rsq_f32_e32 v134, v100
	v_pk_add_f32 v[100:101], v[120:121], 1.0 op_sel_hi:[1,0]
	v_mul_f32_e32 v120, 0x45800000, v134
	v_cndmask_b32_e32 v120, v134, v120, vcc
	v_pk_mul_f32 v[18:19], v[18:19], v[120:121] op_sel_hi:[1,0]
	v_pk_mul_f32 v[16:17], v[16:17], v[120:121] op_sel_hi:[1,0]
	v_pk_mul_f32 v[8:9], v[8:9], v[120:121] op_sel_hi:[1,0]
	v_pk_mul_f32 v[10:11], v[10:11], v[120:121] op_sel_hi:[1,0]
	v_pk_mul_f32 v[32:33], v[32:33], v[120:121] op_sel_hi:[1,0]
	v_pk_mul_f32 v[16:17], v[86:87], v[16:17]
	v_pk_mul_f32 v[18:19], v[88:89], v[18:19]
	v_pk_mul_f32 v[86:87], v[90:91], v[8:9]
	v_pk_mul_f32 v[38:39], v[38:39], v[120:121] op_sel_hi:[1,0]
	v_pk_mul_f32 v[36:37], v[36:37], v[120:121] op_sel_hi:[1,0]
	v_pk_mul_f32 v[34:35], v[34:35], v[120:121] op_sel_hi:[1,0]
	v_pk_mul_f32 v[88:89], v[92:93], v[10:11]
	v_pk_mul_f32 v[90:91], v[110:111], v[32:33]
	v_pk_fma_f32 v[8:9], v[40:41], v[18:19], v[104:105]
	v_pk_fma_f32 v[18:19], v[98:99], v[86:87], v[106:107]
	v_pk_mul_f32 v[40:41], v[114:115], v[36:37]
	v_pk_mul_f32 v[36:37], v[116:117], v[38:39]
	v_pk_add_f32 v[38:39], v[124:125], 1.0 op_sel_hi:[1,0]
	v_pk_add_f32 v[86:87], v[122:123], 1.0 op_sel_hi:[1,0]
	v_pk_mul_f32 v[32:33], v[112:113], v[34:35]
	v_pk_fma_f32 v[10:11], v[94:95], v[16:17], v[102:103]
	v_pk_fma_f32 v[16:17], v[96:97], v[88:89], v[108:109]
	v_pk_fma_f32 v[34:35], v[118:119], v[90:91], v[126:127]
	v_pk_fma_f32 v[36:37], v[38:39], v[36:37], v[132:133]
	v_pk_fma_f32 v[38:39], v[86:87], v[40:41], v[130:131]
	ds_read_b128 v[86:89], v77 offset:4096
	ds_read_b128 v[90:93], v82 offset:12288
	ds_read_b128 v[94:97], v82 offset:4096
	v_pk_mul_f32 v[22:23], v[22:23], v[120:121] op_sel_hi:[1,0]
	v_pk_mul_f32 v[20:21], v[20:21], v[120:121] op_sel_hi:[1,0]
	v_pk_fma_f32 v[32:33], v[100:101], v[32:33], v[128:129]
	ds_read_b128 v[98:101], v77 offset:5120
	s_waitcnt lgkmcnt(3)
	v_pk_mul_f32 v[40:41], v[86:87], v[20:21]
	v_pk_mul_f32 v[20:21], v[88:89], v[22:23]
	ds_read_b128 v[86:89], v82 offset:13312
	s_waitcnt lgkmcnt(3)
	v_pk_add_f32 v[22:23], v[92:93], 1.0 op_sel_hi:[1,0]
	v_pk_add_f32 v[102:103], v[90:91], 1.0 op_sel_hi:[1,0]
	ds_read_b128 v[90:93], v82 offset:5120
	v_pk_mul_f32 v[14:15], v[14:15], v[120:121] op_sel_hi:[1,0]
	v_pk_mul_f32 v[12:13], v[12:13], v[120:121] op_sel_hi:[1,0]
	s_waitcnt lgkmcnt(3)
	v_pk_fma_f32 v[20:21], v[22:23], v[20:21], v[96:97]
	v_pk_fma_f32 v[22:23], v[102:103], v[40:41], v[94:95]
	s_waitcnt lgkmcnt(2)
	v_pk_mul_f32 v[40:41], v[12:13], v[98:99]
	v_pk_mul_f32 v[12:13], v[14:15], v[100:101]
	s_waitcnt lgkmcnt(1)
	v_pk_add_f32 v[14:15], v[88:89], 1.0 op_sel_hi:[1,0]
	v_pk_add_f32 v[86:87], v[86:87], 1.0 op_sel_hi:[1,0]
	s_waitcnt lgkmcnt(0)
	v_pk_fma_f32 v[12:13], v[12:13], v[14:15], v[92:93]
	v_pk_fma_f32 v[14:15], v[40:41], v[86:87], v[90:91]
	ds_read_b128 v[86:89], v77 offset:6144
	ds_read_b128 v[90:93], v82 offset:14336
	ds_read_b128 v[94:97], v82 offset:6144
	v_pk_mul_f32 v[6:7], v[6:7], v[120:121] op_sel_hi:[1,0]
	v_pk_mul_f32 v[4:5], v[4:5], v[120:121] op_sel_hi:[1,0]
	ds_read_b128 v[98:101], v77 offset:7168
	s_waitcnt lgkmcnt(3)
	v_pk_mul_f32 v[40:41], v[4:5], v[86:87]
	v_pk_mul_f32 v[4:5], v[6:7], v[88:89]
	ds_read_b128 v[86:89], v82 offset:15360
	s_waitcnt lgkmcnt(3)
	v_pk_add_f32 v[6:7], v[92:93], 1.0 op_sel_hi:[1,0]
	v_pk_add_f32 v[102:103], v[90:91], 1.0 op_sel_hi:[1,0]
	ds_read_b128 v[90:93], v82 offset:7168
	v_pk_mul_f32 v[2:3], v[2:3], v[120:121] op_sel_hi:[1,0]
	v_pk_mul_f32 v[0:1], v[0:1], v[120:121] op_sel_hi:[1,0]
	s_waitcnt lgkmcnt(3)
	v_pk_fma_f32 v[4:5], v[4:5], v[6:7], v[96:97]
	v_pk_fma_f32 v[6:7], v[40:41], v[102:103], v[94:95]
	s_waitcnt lgkmcnt(2)
	v_pk_mul_f32 v[40:41], v[0:1], v[98:99]
	v_pk_mul_f32 v[0:1], v[2:3], v[100:101]
	s_waitcnt lgkmcnt(1)
	v_pk_add_f32 v[2:3], v[88:89], 1.0 op_sel_hi:[1,0]
	v_pk_add_f32 v[86:87], v[86:87], 1.0 op_sel_hi:[1,0]
	s_waitcnt lgkmcnt(0)
	v_pk_fma_f32 v[0:1], v[0:1], v[2:3], v[92:93]
	v_pk_fma_f32 v[2:3], v[40:41], v[86:87], v[90:91]
	v_cmp_lt_i32_e32 vcc, -1, v83
	s_and_saveexec_b64 s[14:15], vcc
	s_cbranch_execz .LBB0_134
	ds_read_b128 v[86:89], v78
	v_sub_f32_e32 v43, v43, v11
	v_sub_f32_e32 v42, v42, v10
	v_lshlrev_b64 v[40:41], 12, v[30:31]
	v_sub_f32_e32 v47, v47, v9
	v_sub_f32_e32 v46, v46, v8
	s_waitcnt lgkmcnt(0)
	v_pk_fma_f32 v[86:87], v[42:43], v[86:87], v[10:11]
	v_lshl_add_u64 v[40:41], v[28:29], 0, v[40:41]
	v_pk_fma_f32 v[88:89], v[46:47], v[88:89], v[8:9]
	v_cvt_pk_bf16_f32 v86, v86, v87
	v_sub_f32_e32 v45, v45, v19
	v_cvt_pk_bf16_f32 v87, v88, v89
	global_store_dwordx2 v[40:41], v[86:87], off nt
	ds_read_b128 v[86:89], v78 offset:1024
	v_sub_f32_e32 v44, v44, v18
	v_sub_f32_e32 v49, v49, v17
	v_sub_f32_e32 v48, v48, v16
	v_sub_f32_e32 v51, v51, v35
	s_waitcnt lgkmcnt(0)
	v_pk_fma_f32 v[86:87], v[44:45], v[86:87], v[18:19]
	v_pk_fma_f32 v[88:89], v[48:49], v[88:89], v[16:17]
	v_cvt_pk_bf16_f32 v86, v86, v87
	v_sub_f32_e32 v50, v50, v34
	v_cvt_pk_bf16_f32 v87, v88, v89
	global_store_dwordx2 v[40:41], v[86:87], off offset:512 nt
	ds_read_b128 v[86:89], v78 offset:2048
	v_sub_f32_e32 v53, v53, v33
	v_sub_f32_e32 v52, v52, v32
	v_sub_f32_e32 v55, v55, v39
	v_sub_f32_e32 v54, v54, v38
	s_waitcnt lgkmcnt(0)
	v_pk_fma_f32 v[86:87], v[50:51], v[86:87], v[34:35]
	v_pk_fma_f32 v[88:89], v[52:53], v[88:89], v[32:33]
	v_cvt_pk_bf16_f32 v86, v86, v87
	v_sub_f32_e32 v57, v57, v37
	v_cvt_pk_bf16_f32 v87, v88, v89
	global_store_dwordx2 v[40:41], v[86:87], off offset:1024 nt
	ds_read_b128 v[86:89], v78 offset:3072
	v_sub_f32_e32 v56, v56, v36
	v_sub_f32_e32 v59, v59, v23
	v_sub_f32_e32 v58, v58, v22
	v_sub_f32_e32 v61, v61, v21
	s_waitcnt lgkmcnt(0)
	v_pk_fma_f32 v[86:87], v[54:55], v[86:87], v[38:39]
	v_pk_fma_f32 v[88:89], v[56:57], v[88:89], v[36:37]
	v_cvt_pk_bf16_f32 v86, v86, v87
	v_sub_f32_e32 v60, v60, v20
	v_cvt_pk_bf16_f32 v87, v88, v89
	global_store_dwordx2 v[40:41], v[86:87], off offset:1536 nt
	ds_read_b128 v[86:89], v78 offset:4096
	v_sub_f32_e32 v63, v63, v15
	v_sub_f32_e32 v62, v62, v14
	v_sub_f32_e32 v65, v65, v13
	v_sub_f32_e32 v64, v64, v12
	s_waitcnt lgkmcnt(0)
	v_pk_fma_f32 v[86:87], v[58:59], v[86:87], v[22:23]
	v_pk_fma_f32 v[88:89], v[60:61], v[88:89], v[20:21]
	v_cvt_pk_bf16_f32 v86, v86, v87
	v_sub_f32_e32 v67, v67, v7
	v_cvt_pk_bf16_f32 v87, v88, v89
	global_store_dwordx2 v[40:41], v[86:87], off offset:2048 nt
	ds_read_b128 v[86:89], v78 offset:5120
	v_sub_f32_e32 v66, v66, v6
	v_sub_f32_e32 v69, v69, v5
	v_sub_f32_e32 v68, v68, v4
	v_sub_f32_e32 v71, v71, v3
	s_waitcnt lgkmcnt(0)
	v_pk_fma_f32 v[86:87], v[62:63], v[86:87], v[14:15]
	v_pk_fma_f32 v[88:89], v[64:65], v[88:89], v[12:13]
	v_cvt_pk_bf16_f32 v86, v86, v87
	v_sub_f32_e32 v70, v70, v2
	v_cvt_pk_bf16_f32 v87, v88, v89
	global_store_dwordx2 v[40:41], v[86:87], off offset:2560 nt
	ds_read_b128 v[86:89], v78 offset:6144
	v_sub_f32_e32 v73, v73, v1
	v_sub_f32_e32 v72, v72, v0
	v_add_co_u32_e32 v92, vcc, s16, v40
	s_waitcnt lgkmcnt(0)
	v_pk_fma_f32 v[86:87], v[66:67], v[86:87], v[6:7]
	v_pk_fma_f32 v[88:89], v[68:69], v[88:89], v[4:5]
	v_cvt_pk_bf16_f32 v86, v86, v87
	v_addc_co_u32_e32 v93, vcc, 0, v41, vcc
	v_cvt_pk_bf16_f32 v87, v88, v89
	global_store_dwordx2 v[40:41], v[86:87], off offset:3072 nt
	ds_read_b128 v[86:89], v78 offset:7168
	s_waitcnt lgkmcnt(0)
	v_pk_fma_f32 v[86:87], v[70:71], v[86:87], v[2:3]
	v_pk_fma_f32 v[88:89], v[72:73], v[88:89], v[0:1]
	v_cvt_pk_bf16_f32 v86, v86, v87
	s_nop 0
	v_cvt_pk_bf16_f32 v87, v88, v89
	global_store_dwordx2 v[40:41], v[86:87], off offset:3584 nt
	ds_read_b128 v[86:89], v78 offset:8192
	s_waitcnt lgkmcnt(0)
	v_pk_fma_f32 v[88:89], v[46:47], v[88:89], v[8:9]
	v_pk_fma_f32 v[86:87], v[42:43], v[86:87], v[10:11]
	s_nop 0
	v_cvt_pk_bf16_f32 v90, v86, v87
	v_cvt_pk_bf16_f32 v91, v88, v89
	ds_read_b128 v[86:89], v78 offset:9216
	global_store_dwordx2 v[92:93], v[90:91], off nt
	s_waitcnt lgkmcnt(0)
	v_pk_fma_f32 v[88:89], v[48:49], v[88:89], v[16:17]
	v_pk_fma_f32 v[86:87], v[44:45], v[86:87], v[18:19]
	s_nop 0
	v_cvt_pk_bf16_f32 v90, v86, v87
	v_cvt_pk_bf16_f32 v91, v88, v89
	ds_read_b128 v[86:89], v78 offset:10240
	global_store_dwordx2 v[92:93], v[90:91], off offset:512 nt
	s_waitcnt lgkmcnt(0)
	v_pk_fma_f32 v[88:89], v[52:53], v[88:89], v[32:33]
	v_pk_fma_f32 v[86:87], v[50:51], v[86:87], v[34:35]
	s_nop 0
	v_cvt_pk_bf16_f32 v90, v86, v87
	v_cvt_pk_bf16_f32 v91, v88, v89
	ds_read_b128 v[86:89], v78 offset:11264
	global_store_dwordx2 v[92:93], v[90:91], off offset:1024 nt
	s_waitcnt lgkmcnt(0)
	v_pk_fma_f32 v[88:89], v[56:57], v[88:89], v[36:37]
	v_pk_fma_f32 v[86:87], v[54:55], v[86:87], v[38:39]
	s_nop 0
	v_cvt_pk_bf16_f32 v90, v86, v87
	v_cvt_pk_bf16_f32 v91, v88, v89
	ds_read_b128 v[86:89], v78 offset:12288
	global_store_dwordx2 v[92:93], v[90:91], off offset:1536 nt
	s_waitcnt lgkmcnt(0)
	v_pk_fma_f32 v[88:89], v[60:61], v[88:89], v[20:21]
	v_pk_fma_f32 v[86:87], v[58:59], v[86:87], v[22:23]
	s_nop 0
	v_cvt_pk_bf16_f32 v90, v86, v87
	v_cvt_pk_bf16_f32 v91, v88, v89
	ds_read_b128 v[86:89], v78 offset:13312
	global_store_dwordx2 v[92:93], v[90:91], off offset:2048 nt
	s_waitcnt lgkmcnt(0)
	v_pk_fma_f32 v[88:89], v[64:65], v[88:89], v[12:13]
	v_pk_fma_f32 v[86:87], v[62:63], v[86:87], v[14:15]
	s_nop 0
	v_cvt_pk_bf16_f32 v90, v86, v87
	v_cvt_pk_bf16_f32 v91, v88, v89
	ds_read_b128 v[86:89], v78 offset:14336
	global_store_dwordx2 v[92:93], v[90:91], off offset:2560 nt
	s_waitcnt lgkmcnt(0)
	v_pk_fma_f32 v[88:89], v[68:69], v[88:89], v[4:5]
	v_pk_fma_f32 v[86:87], v[66:67], v[86:87], v[6:7]
	s_nop 0
	v_cvt_pk_bf16_f32 v90, v86, v87
	v_cvt_pk_bf16_f32 v91, v88, v89
	ds_read_b128 v[86:89], v78 offset:15360
	global_store_dwordx2 v[92:93], v[90:91], off offset:3072 nt
	s_waitcnt lgkmcnt(0)
	v_pk_fma_f32 v[86:87], v[70:71], v[86:87], v[2:3]
	v_pk_fma_f32 v[88:89], v[72:73], v[88:89], v[0:1]
	v_cvt_pk_bf16_f32 v86, v86, v87
	s_nop 0
	v_cvt_pk_bf16_f32 v87, v88, v89
	global_store_dwordx2 v[92:93], v[86:87], off offset:3584 nt
	ds_read_b128 v[86:89], v78 offset:16384
	v_add_co_u32_e32 v92, vcc, s17, v40
	s_waitcnt lgkmcnt(0)
	v_pk_fma_f32 v[88:89], v[46:47], v[88:89], v[8:9]
	v_pk_fma_f32 v[86:87], v[42:43], v[86:87], v[10:11]
	v_addc_co_u32_e32 v93, vcc, 0, v41, vcc
	v_cvt_pk_bf16_f32 v90, v86, v87
	v_cvt_pk_bf16_f32 v91, v88, v89
	ds_read_b128 v[86:89], v78 offset:17408
	global_store_dwordx2 v[92:93], v[90:91], off nt
	s_waitcnt lgkmcnt(0)
	v_pk_fma_f32 v[88:89], v[48:49], v[88:89], v[16:17]
	v_pk_fma_f32 v[86:87], v[44:45], v[86:87], v[18:19]
	s_nop 0
	v_cvt_pk_bf16_f32 v90, v86, v87
	v_cvt_pk_bf16_f32 v91, v88, v89
	ds_read_b128 v[86:89], v78 offset:18432
	global_store_dwordx2 v[92:93], v[90:91], off offset:512 nt
	s_waitcnt lgkmcnt(0)
	v_pk_fma_f32 v[88:89], v[52:53], v[88:89], v[32:33]
	v_pk_fma_f32 v[86:87], v[50:51], v[86:87], v[34:35]
	s_nop 0
	v_cvt_pk_bf16_f32 v90, v86, v87
	v_cvt_pk_bf16_f32 v91, v88, v89
	ds_read_b128 v[86:89], v78 offset:19456
	global_store_dwordx2 v[92:93], v[90:91], off offset:1024 nt
	s_waitcnt lgkmcnt(0)
	v_pk_fma_f32 v[88:89], v[56:57], v[88:89], v[36:37]
	v_pk_fma_f32 v[86:87], v[54:55], v[86:87], v[38:39]
	s_nop 0
	v_cvt_pk_bf16_f32 v90, v86, v87
	v_cvt_pk_bf16_f32 v91, v88, v89
	ds_read_b128 v[86:89], v78 offset:20480
	global_store_dwordx2 v[92:93], v[90:91], off offset:1536 nt
	s_waitcnt lgkmcnt(0)
	v_pk_fma_f32 v[88:89], v[60:61], v[88:89], v[20:21]
	v_pk_fma_f32 v[86:87], v[58:59], v[86:87], v[22:23]
	s_nop 0
	v_cvt_pk_bf16_f32 v90, v86, v87
	v_cvt_pk_bf16_f32 v91, v88, v89
	ds_read_b128 v[86:89], v78 offset:21504
	global_store_dwordx2 v[92:93], v[90:91], off offset:2048 nt
	s_waitcnt lgkmcnt(0)
	v_pk_fma_f32 v[88:89], v[64:65], v[88:89], v[12:13]
	v_pk_fma_f32 v[86:87], v[62:63], v[86:87], v[14:15]
	s_nop 0
	v_cvt_pk_bf16_f32 v90, v86, v87
	v_cvt_pk_bf16_f32 v91, v88, v89
	ds_read_b128 v[86:89], v78 offset:22528
	global_store_dwordx2 v[92:93], v[90:91], off offset:2560 nt
	s_waitcnt lgkmcnt(0)
	v_pk_fma_f32 v[88:89], v[68:69], v[88:89], v[4:5]
	v_pk_fma_f32 v[86:87], v[66:67], v[86:87], v[6:7]
	s_nop 0
	v_cvt_pk_bf16_f32 v90, v86, v87
	v_cvt_pk_bf16_f32 v91, v88, v89
	ds_read_b128 v[86:89], v78 offset:23552
	global_store_dwordx2 v[92:93], v[90:91], off offset:3072 nt
	s_waitcnt lgkmcnt(0)
	v_pk_fma_f32 v[86:87], v[70:71], v[86:87], v[2:3]
	v_pk_fma_f32 v[88:89], v[72:73], v[88:89], v[0:1]
	v_cvt_pk_bf16_f32 v86, v86, v87
	s_nop 0
	v_cvt_pk_bf16_f32 v87, v88, v89
	global_store_dwordx2 v[92:93], v[86:87], off offset:3584 nt
	ds_read_b128 v[86:89], v78 offset:24576
	v_add_co_u32_e32 v92, vcc, s18, v40
	s_waitcnt lgkmcnt(0)
	v_pk_fma_f32 v[88:89], v[46:47], v[88:89], v[8:9]
	v_pk_fma_f32 v[86:87], v[42:43], v[86:87], v[10:11]
	v_addc_co_u32_e32 v93, vcc, 0, v41, vcc
	v_cvt_pk_bf16_f32 v90, v86, v87
	v_cvt_pk_bf16_f32 v91, v88, v89
	ds_read_b128 v[86:89], v78 offset:25600
	global_store_dwordx2 v[92:93], v[90:91], off nt
	s_waitcnt lgkmcnt(0)
	v_pk_fma_f32 v[88:89], v[48:49], v[88:89], v[16:17]
	v_pk_fma_f32 v[86:87], v[44:45], v[86:87], v[18:19]
	s_nop 0
	v_cvt_pk_bf16_f32 v90, v86, v87
	v_cvt_pk_bf16_f32 v91, v88, v89
	ds_read_b128 v[86:89], v78 offset:26624
	global_store_dwordx2 v[92:93], v[90:91], off offset:512 nt
	s_waitcnt lgkmcnt(0)
	v_pk_fma_f32 v[88:89], v[52:53], v[88:89], v[32:33]
	v_pk_fma_f32 v[86:87], v[50:51], v[86:87], v[34:35]
	s_nop 0
	v_cvt_pk_bf16_f32 v90, v86, v87
	v_cvt_pk_bf16_f32 v91, v88, v89
	ds_read_b128 v[86:89], v78 offset:27648
	global_store_dwordx2 v[92:93], v[90:91], off offset:1024 nt
	s_waitcnt lgkmcnt(0)
	v_pk_fma_f32 v[88:89], v[56:57], v[88:89], v[36:37]
	v_pk_fma_f32 v[86:87], v[54:55], v[86:87], v[38:39]
	s_nop 0
	v_cvt_pk_bf16_f32 v90, v86, v87
	v_cvt_pk_bf16_f32 v91, v88, v89
	ds_read_b128 v[86:89], v78 offset:28672
	global_store_dwordx2 v[92:93], v[90:91], off offset:1536 nt
	s_waitcnt lgkmcnt(0)
	v_pk_fma_f32 v[88:89], v[60:61], v[88:89], v[20:21]
	v_pk_fma_f32 v[86:87], v[58:59], v[86:87], v[22:23]
	s_nop 0
	v_cvt_pk_bf16_f32 v90, v86, v87
	v_cvt_pk_bf16_f32 v91, v88, v89
	ds_read_b128 v[86:89], v78 offset:29696
	global_store_dwordx2 v[92:93], v[90:91], off offset:2048 nt
	s_waitcnt lgkmcnt(0)
	v_pk_fma_f32 v[88:89], v[64:65], v[88:89], v[12:13]
	v_pk_fma_f32 v[86:87], v[62:63], v[86:87], v[14:15]
	s_nop 0
	v_cvt_pk_bf16_f32 v90, v86, v87
	v_cvt_pk_bf16_f32 v91, v88, v89
	ds_read_b128 v[86:89], v78 offset:30720
	global_store_dwordx2 v[92:93], v[90:91], off offset:2560 nt
	s_waitcnt lgkmcnt(0)
	v_pk_fma_f32 v[88:89], v[68:69], v[88:89], v[4:5]
	v_pk_fma_f32 v[86:87], v[66:67], v[86:87], v[6:7]
	s_nop 0
	v_cvt_pk_bf16_f32 v90, v86, v87
	v_cvt_pk_bf16_f32 v91, v88, v89
	ds_read_b128 v[86:89], v78 offset:31744
	global_store_dwordx2 v[92:93], v[90:91], off offset:3072 nt
	s_waitcnt lgkmcnt(0)
	v_pk_fma_f32 v[86:87], v[70:71], v[86:87], v[2:3]
	v_pk_fma_f32 v[88:89], v[72:73], v[88:89], v[0:1]
	v_cvt_pk_bf16_f32 v86, v86, v87
	s_nop 0
	v_cvt_pk_bf16_f32 v87, v88, v89
	global_store_dwordx2 v[92:93], v[86:87], off offset:3584 nt
	ds_read_b128 v[86:89], v78 offset:32768
	v_add_co_u32_e32 v92, vcc, s19, v40
	s_waitcnt lgkmcnt(0)
	v_pk_fma_f32 v[88:89], v[46:47], v[88:89], v[8:9]
	v_pk_fma_f32 v[86:87], v[42:43], v[86:87], v[10:11]
	v_addc_co_u32_e32 v93, vcc, 0, v41, vcc
	v_cvt_pk_bf16_f32 v90, v86, v87
	v_cvt_pk_bf16_f32 v91, v88, v89
	ds_read_b128 v[86:89], v78 offset:33792
	global_store_dwordx2 v[92:93], v[90:91], off nt
	s_waitcnt lgkmcnt(0)
	v_pk_fma_f32 v[88:89], v[48:49], v[88:89], v[16:17]
	v_pk_fma_f32 v[86:87], v[44:45], v[86:87], v[18:19]
	s_nop 0
	v_cvt_pk_bf16_f32 v90, v86, v87
	v_cvt_pk_bf16_f32 v91, v88, v89
	ds_read_b128 v[86:89], v78 offset:34816
	global_store_dwordx2 v[92:93], v[90:91], off offset:512 nt
	s_waitcnt lgkmcnt(0)
	v_pk_fma_f32 v[88:89], v[52:53], v[88:89], v[32:33]
	v_pk_fma_f32 v[86:87], v[50:51], v[86:87], v[34:35]
	s_nop 0
	v_cvt_pk_bf16_f32 v90, v86, v87
	v_cvt_pk_bf16_f32 v91, v88, v89
	ds_read_b128 v[86:89], v78 offset:35840
	global_store_dwordx2 v[92:93], v[90:91], off offset:1024 nt
	s_waitcnt lgkmcnt(0)
	v_pk_fma_f32 v[88:89], v[56:57], v[88:89], v[36:37]
	v_pk_fma_f32 v[86:87], v[54:55], v[86:87], v[38:39]
	s_nop 0
	v_cvt_pk_bf16_f32 v90, v86, v87
	v_cvt_pk_bf16_f32 v91, v88, v89
	ds_read_b128 v[86:89], v78 offset:36864
	global_store_dwordx2 v[92:93], v[90:91], off offset:1536 nt
	s_waitcnt lgkmcnt(0)
	v_pk_fma_f32 v[88:89], v[60:61], v[88:89], v[20:21]
	v_pk_fma_f32 v[86:87], v[58:59], v[86:87], v[22:23]
	s_nop 0
	v_cvt_pk_bf16_f32 v90, v86, v87
	v_cvt_pk_bf16_f32 v91, v88, v89
	ds_read_b128 v[86:89], v78 offset:37888
	global_store_dwordx2 v[92:93], v[90:91], off offset:2048 nt
	s_waitcnt lgkmcnt(0)
	v_pk_fma_f32 v[88:89], v[64:65], v[88:89], v[12:13]
	v_pk_fma_f32 v[86:87], v[62:63], v[86:87], v[14:15]
	s_nop 0
	v_cvt_pk_bf16_f32 v90, v86, v87
	v_cvt_pk_bf16_f32 v91, v88, v89
	ds_read_b128 v[86:89], v78 offset:38912
	global_store_dwordx2 v[92:93], v[90:91], off offset:2560 nt
	s_waitcnt lgkmcnt(0)
	v_pk_fma_f32 v[88:89], v[68:69], v[88:89], v[4:5]
	v_pk_fma_f32 v[86:87], v[66:67], v[86:87], v[6:7]
	s_nop 0
	v_cvt_pk_bf16_f32 v90, v86, v87
	v_cvt_pk_bf16_f32 v91, v88, v89
	ds_read_b128 v[86:89], v78 offset:39936
	global_store_dwordx2 v[92:93], v[90:91], off offset:3072 nt
	s_waitcnt lgkmcnt(0)
	v_pk_fma_f32 v[86:87], v[70:71], v[86:87], v[2:3]
	v_pk_fma_f32 v[88:89], v[72:73], v[88:89], v[0:1]
	v_cvt_pk_bf16_f32 v86, v86, v87
	s_nop 0
	v_cvt_pk_bf16_f32 v87, v88, v89
	global_store_dwordx2 v[92:93], v[86:87], off offset:3584 nt
	ds_read_b128 v[86:89], v78 offset:40960
	s_waitcnt lgkmcnt(0)
	v_pk_fma_f32 v[42:43], v[42:43], v[86:87], v[10:11]
	v_pk_fma_f32 v[46:47], v[46:47], v[88:89], v[8:9]
	v_cvt_pk_bf16_f32 v42, v42, v43
	s_nop 0
	v_cvt_pk_bf16_f32 v43, v46, v47
	ds_read_b128 v[86:89], v78 offset:41984
	v_add_co_u32_e32 v46, vcc, s20, v40
	s_nop 1
	v_addc_co_u32_e32 v47, vcc, 0, v41, vcc
	global_store_dwordx2 v[46:47], v[42:43], off nt
	s_waitcnt lgkmcnt(0)
	v_pk_fma_f32 v[40:41], v[48:49], v[88:89], v[16:17]
	v_pk_fma_f32 v[42:43], v[44:45], v[86:87], v[18:19]
	s_nop 0
	v_cvt_pk_bf16_f32 v44, v42, v43
	v_cvt_pk_bf16_f32 v45, v40, v41
	ds_read_b128 v[40:43], v78 offset:43008
	global_store_dwordx2 v[46:47], v[44:45], off offset:512 nt
	s_waitcnt lgkmcnt(0)
	v_pk_fma_f32 v[42:43], v[52:53], v[42:43], v[32:33]
	v_pk_fma_f32 v[40:41], v[50:51], v[40:41], v[34:35]
	s_nop 0
	v_cvt_pk_bf16_f32 v44, v40, v41
	v_cvt_pk_bf16_f32 v45, v42, v43
	ds_read_b128 v[40:43], v78 offset:44032
	global_store_dwordx2 v[46:47], v[44:45], off offset:1024 nt
	s_waitcnt lgkmcnt(0)
	v_pk_fma_f32 v[42:43], v[56:57], v[42:43], v[36:37]
	v_pk_fma_f32 v[40:41], v[54:55], v[40:41], v[38:39]
	s_nop 0
	v_cvt_pk_bf16_f32 v44, v40, v41
	v_cvt_pk_bf16_f32 v45, v42, v43
	ds_read_b128 v[40:43], v78 offset:45056
	global_store_dwordx2 v[46:47], v[44:45], off offset:1536 nt
	s_waitcnt lgkmcnt(0)
	v_pk_fma_f32 v[42:43], v[60:61], v[42:43], v[20:21]
	v_pk_fma_f32 v[40:41], v[58:59], v[40:41], v[22:23]
	s_nop 0
	v_cvt_pk_bf16_f32 v44, v40, v41
	v_cvt_pk_bf16_f32 v45, v42, v43
	ds_read_b128 v[40:43], v78 offset:46080
	global_store_dwordx2 v[46:47], v[44:45], off offset:2048 nt
	s_waitcnt lgkmcnt(0)
	v_pk_fma_f32 v[42:43], v[64:65], v[42:43], v[12:13]
	v_pk_fma_f32 v[40:41], v[62:63], v[40:41], v[14:15]
	s_nop 0
	v_cvt_pk_bf16_f32 v44, v40, v41
	v_cvt_pk_bf16_f32 v45, v42, v43
	ds_read_b128 v[40:43], v78 offset:47104
	global_store_dwordx2 v[46:47], v[44:45], off offset:2560 nt
	s_waitcnt lgkmcnt(0)
	v_pk_fma_f32 v[42:43], v[68:69], v[42:43], v[4:5]
	v_pk_fma_f32 v[40:41], v[66:67], v[40:41], v[6:7]
	s_nop 0
	v_cvt_pk_bf16_f32 v44, v40, v41
	v_cvt_pk_bf16_f32 v45, v42, v43
	ds_read_b128 v[40:43], v78 offset:48128
	global_store_dwordx2 v[46:47], v[44:45], off offset:3072 nt
	s_waitcnt lgkmcnt(0)
	v_pk_fma_f32 v[40:41], v[70:71], v[40:41], v[2:3]
	v_pk_fma_f32 v[42:43], v[72:73], v[42:43], v[0:1]
	v_cvt_pk_bf16_f32 v40, v40, v41
	s_nop 0
	v_cvt_pk_bf16_f32 v41, v42, v43
	global_store_dwordx2 v[46:47], v[40:41], off offset:3584 nt
	s_and_b64 exec, exec, s[6:7]
	s_cbranch_execz .LBB0_134
	v_lshlrev_b64 v[30:31], 10, v[30:31]
	v_lshl_add_u64 v[30:31], s[4:5], 0, v[30:31]
	v_lshl_add_u64 v[30:31], v[30:31], 0, v[24:25]
	v_add_co_u32_e32 v30, vcc, 0x26000000, v30
	s_nop 1
	v_addc_co_u32_e32 v31, vcc, 0, v31, vcc
	global_store_dwordx2 v[30:31], v[84:85], off offset:896 nt
	s_branch .LBB0_134
